# P5 residual epilogue: all X loads issued in batches with counted vmcnt instead of one wait per load
# speedup vs baseline: 1.0182x; 1.0067x over previous
.LBB0_961:
	v_lshl_add_u32 v140, s16, 8, v142
	v_lshl_or_b32 v138, s18, 8, v144
	v_ashrrev_i32_e32 v141, 31, v140
	v_ashrrev_i32_e32 v139, 31, v138
	v_lshlrev_b64 v[148:149], 10, v[140:141]
	v_lshl_add_u64 v[150:151], v[148:149], 0, v[138:139]
	v_lshl_add_u64 v[138:139], v[150:151], 2, s[8:9]
	v_lshl_add_u64 v[140:141], v[150:151], 1, s[20:21]
	s_mov_b64 s[94:95], 0x10000
	s_mov_b64 s[96:97], 0x50000
	s_mov_b64 s[98:99], 0x8000
	s_mov_b64 s[100:101], 0x28000
	global_load_dwordx4 v[152:155], v[138:139], off nt
	global_load_dwordx4 v[156:159], v[138:139], off offset:64 nt
	global_load_dwordx4 v[160:163], v[138:139], off offset:512 nt
	global_load_dwordx4 v[164:167], v[138:139], off offset:576 nt
	v_lshl_add_u64 v[138:139], v[138:139], 0, s[94:95]
	global_load_dwordx4 v[168:171], v[138:139], off nt
	global_load_dwordx4 v[172:175], v[138:139], off offset:64 nt
	global_load_dwordx4 v[176:179], v[138:139], off offset:512 nt
	global_load_dwordx4 v[180:183], v[138:139], off offset:576 nt
	v_lshl_add_u64 v[138:139], v[138:139], 0, s[94:95]
	global_load_dwordx4 v[184:187], v[138:139], off nt
	global_load_dwordx4 v[188:191], v[138:139], off offset:64 nt
	global_load_dwordx4 v[192:195], v[138:139], off offset:512 nt
	global_load_dwordx4 v[196:199], v[138:139], off offset:576 nt
	v_lshl_add_u64 v[138:139], v[138:139], 0, s[94:95]
	global_load_dwordx4 v[200:203], v[138:139], off nt
	global_load_dwordx4 v[204:207], v[138:139], off offset:64 nt
	global_load_dwordx4 v[208:211], v[138:139], off offset:512 nt
	global_load_dwordx4 v[212:215], v[138:139], off offset:576 nt
	v_lshl_add_u64 v[138:139], v[138:139], 0, s[96:97]
	global_load_dwordx4 v[216:219], v[138:139], off nt
	global_load_dwordx4 v[220:223], v[138:139], off offset:64 nt
	global_load_dwordx4 v[224:227], v[138:139], off offset:512 nt
	global_load_dwordx4 v[228:231], v[138:139], off offset:576 nt
	v_lshl_add_u64 v[138:139], v[138:139], 0, s[94:95]
	global_load_dwordx4 v[232:235], v[138:139], off nt
	global_load_dwordx4 v[236:239], v[138:139], off offset:64 nt
	global_load_dwordx4 v[240:243], v[138:139], off offset:512 nt
	global_load_dwordx4 v[244:247], v[138:139], off offset:576 nt
	v_lshl_add_u64 v[138:139], v[138:139], 0, s[94:95]
	s_waitcnt vmcnt(23)
	v_add_f32_e32 v124, v124, v152
	v_add_f32_e32 v125, v125, v153
	v_add_f32_e32 v126, v126, v154
	v_add_f32_e32 v127, v127, v155
	v_cvt_pk_bf16_f32 v124, v124, v125
	v_cvt_pk_bf16_f32 v125, v126, v127
	global_store_dwordx2 v[140:141], v[124:125], off
	s_waitcnt vmcnt(23)
	v_add_f32_e32 v120, v120, v156
	v_add_f32_e32 v121, v121, v157
	v_add_f32_e32 v122, v122, v158
	v_add_f32_e32 v123, v123, v159
	v_cvt_pk_bf16_f32 v120, v120, v121
	v_cvt_pk_bf16_f32 v121, v122, v123
	global_store_dwordx2 v[140:141], v[120:121], off offset:32
	s_waitcnt vmcnt(23)
	v_add_f32_e32 v116, v116, v160
	v_add_f32_e32 v117, v117, v161
	v_add_f32_e32 v118, v118, v162
	v_add_f32_e32 v119, v119, v163
	v_cvt_pk_bf16_f32 v116, v116, v117
	v_cvt_pk_bf16_f32 v117, v118, v119
	global_store_dwordx2 v[140:141], v[116:117], off offset:256
	s_waitcnt vmcnt(23)
	v_add_f32_e32 v108, v108, v164
	v_add_f32_e32 v109, v109, v165
	v_add_f32_e32 v110, v110, v166
	v_add_f32_e32 v111, v111, v167
	v_cvt_pk_bf16_f32 v108, v108, v109
	v_cvt_pk_bf16_f32 v109, v110, v111
	global_store_dwordx2 v[140:141], v[108:109], off offset:288
	v_lshl_add_u64 v[140:141], v[140:141], 0, s[98:99]
	s_waitcnt vmcnt(23)
	v_add_f32_e32 v112, v112, v168
	v_add_f32_e32 v113, v113, v169
	v_add_f32_e32 v114, v114, v170
	v_add_f32_e32 v115, v115, v171
	v_cvt_pk_bf16_f32 v112, v112, v113
	v_cvt_pk_bf16_f32 v113, v114, v115
	global_store_dwordx2 v[140:141], v[112:113], off
	s_waitcnt vmcnt(23)
	v_add_f32_e32 v104, v104, v172
	v_add_f32_e32 v105, v105, v173
	v_add_f32_e32 v106, v106, v174
	v_add_f32_e32 v107, v107, v175
	v_cvt_pk_bf16_f32 v104, v104, v105
	v_cvt_pk_bf16_f32 v105, v106, v107
	global_store_dwordx2 v[140:141], v[104:105], off offset:32
	s_waitcnt vmcnt(23)
	v_add_f32_e32 v100, v100, v176
	v_add_f32_e32 v101, v101, v177
	v_add_f32_e32 v102, v102, v178
	v_add_f32_e32 v103, v103, v179
	v_cvt_pk_bf16_f32 v100, v100, v101
	v_cvt_pk_bf16_f32 v101, v102, v103
	global_store_dwordx2 v[140:141], v[100:101], off offset:256
	s_waitcnt vmcnt(23)
	v_add_f32_e32 v92, v92, v180
	v_add_f32_e32 v93, v93, v181
	v_add_f32_e32 v94, v94, v182
	v_add_f32_e32 v95, v95, v183
	v_cvt_pk_bf16_f32 v92, v92, v93
	v_cvt_pk_bf16_f32 v93, v94, v95
	global_store_dwordx2 v[140:141], v[92:93], off offset:288
	v_lshl_add_u64 v[140:141], v[140:141], 0, s[98:99]
	global_load_dwordx4 v[124:127], v[138:139], off nt
	global_load_dwordx4 v[120:123], v[138:139], off offset:64 nt
	global_load_dwordx4 v[116:119], v[138:139], off offset:512 nt
	global_load_dwordx4 v[108:111], v[138:139], off offset:576 nt
	v_lshl_add_u64 v[138:139], v[138:139], 0, s[94:95]
	global_load_dwordx4 v[112:115], v[138:139], off nt
	global_load_dwordx4 v[104:107], v[138:139], off offset:64 nt
	global_load_dwordx4 v[100:103], v[138:139], off offset:512 nt
	global_load_dwordx4 v[92:95], v[138:139], off offset:576 nt
	s_waitcnt vmcnt(31)
	v_add_f32_e32 v96, v96, v184
	v_add_f32_e32 v97, v97, v185
	v_add_f32_e32 v98, v98, v186
	v_add_f32_e32 v99, v99, v187
	v_cvt_pk_bf16_f32 v96, v96, v97
	v_cvt_pk_bf16_f32 v97, v98, v99
	global_store_dwordx2 v[140:141], v[96:97], off
	s_waitcnt vmcnt(31)
	v_add_f32_e32 v88, v88, v188
	v_add_f32_e32 v89, v89, v189
	v_add_f32_e32 v90, v90, v190
	v_add_f32_e32 v91, v91, v191
	v_cvt_pk_bf16_f32 v88, v88, v89
	v_cvt_pk_bf16_f32 v89, v90, v91
	global_store_dwordx2 v[140:141], v[88:89], off offset:32
	s_waitcnt vmcnt(31)
	v_add_f32_e32 v84, v84, v192
	v_add_f32_e32 v85, v85, v193
	v_add_f32_e32 v86, v86, v194
	v_add_f32_e32 v87, v87, v195
	v_cvt_pk_bf16_f32 v84, v84, v85
	v_cvt_pk_bf16_f32 v85, v86, v87
	global_store_dwordx2 v[140:141], v[84:85], off offset:256
	s_waitcnt vmcnt(31)
	v_add_f32_e32 v76, v76, v196
	v_add_f32_e32 v77, v77, v197
	v_add_f32_e32 v78, v78, v198
	v_add_f32_e32 v79, v79, v199
	v_cvt_pk_bf16_f32 v76, v76, v77
	v_cvt_pk_bf16_f32 v77, v78, v79
	global_store_dwordx2 v[140:141], v[76:77], off offset:288
	v_lshl_add_u64 v[140:141], v[140:141], 0, s[98:99]
	s_waitcnt vmcnt(31)
	v_add_f32_e32 v80, v80, v200
	v_add_f32_e32 v81, v81, v201
	v_add_f32_e32 v82, v82, v202
	v_add_f32_e32 v83, v83, v203
	v_cvt_pk_bf16_f32 v80, v80, v81
	v_cvt_pk_bf16_f32 v81, v82, v83
	global_store_dwordx2 v[140:141], v[80:81], off
	s_waitcnt vmcnt(31)
	v_add_f32_e32 v72, v72, v204
	v_add_f32_e32 v73, v73, v205
	v_add_f32_e32 v74, v74, v206
	v_add_f32_e32 v75, v75, v207
	v_cvt_pk_bf16_f32 v72, v72, v73
	v_cvt_pk_bf16_f32 v73, v74, v75
	global_store_dwordx2 v[140:141], v[72:73], off offset:32
	s_waitcnt vmcnt(31)
	v_add_f32_e32 v68, v68, v208
	v_add_f32_e32 v69, v69, v209
	v_add_f32_e32 v70, v70, v210
	v_add_f32_e32 v71, v71, v211
	v_cvt_pk_bf16_f32 v68, v68, v69
	v_cvt_pk_bf16_f32 v69, v70, v71
	global_store_dwordx2 v[140:141], v[68:69], off offset:256
	s_waitcnt vmcnt(31)
	v_add_f32_e32 v64, v64, v212
	v_add_f32_e32 v65, v65, v213
	v_add_f32_e32 v66, v66, v214
	v_add_f32_e32 v67, v67, v215
	v_cvt_pk_bf16_f32 v64, v64, v65
	v_cvt_pk_bf16_f32 v65, v66, v67
	global_store_dwordx2 v[140:141], v[64:65], off offset:288
	v_lshl_add_u64 v[140:141], v[140:141], 0, s[100:101]
	s_waitcnt vmcnt(31)
	v_add_f32_e32 v60, v60, v216
	v_add_f32_e32 v61, v61, v217
	v_add_f32_e32 v62, v62, v218
	v_add_f32_e32 v63, v63, v219
	v_cvt_pk_bf16_f32 v60, v60, v61
	v_cvt_pk_bf16_f32 v61, v62, v63
	global_store_dwordx2 v[140:141], v[60:61], off
	s_waitcnt vmcnt(31)
	v_add_f32_e32 v56, v56, v220
	v_add_f32_e32 v57, v57, v221
	v_add_f32_e32 v58, v58, v222
	v_add_f32_e32 v59, v59, v223
	v_cvt_pk_bf16_f32 v56, v56, v57
	v_cvt_pk_bf16_f32 v57, v58, v59
	global_store_dwordx2 v[140:141], v[56:57], off offset:32
	s_waitcnt vmcnt(31)
	v_add_f32_e32 v52, v52, v224
	v_add_f32_e32 v53, v53, v225
	v_add_f32_e32 v54, v54, v226
	v_add_f32_e32 v55, v55, v227
	v_cvt_pk_bf16_f32 v52, v52, v53
	v_cvt_pk_bf16_f32 v53, v54, v55
	global_store_dwordx2 v[140:141], v[52:53], off offset:256
	s_waitcnt vmcnt(31)
	v_add_f32_e32 v44, v44, v228
	v_add_f32_e32 v45, v45, v229
	v_add_f32_e32 v46, v46, v230
	v_add_f32_e32 v47, v47, v231
	v_cvt_pk_bf16_f32 v44, v44, v45
	v_cvt_pk_bf16_f32 v45, v46, v47
	global_store_dwordx2 v[140:141], v[44:45], off offset:288
	v_lshl_add_u64 v[140:141], v[140:141], 0, s[98:99]
	s_waitcnt vmcnt(31)
	v_add_f32_e32 v48, v48, v232
	v_add_f32_e32 v49, v49, v233
	v_add_f32_e32 v50, v50, v234
	v_add_f32_e32 v51, v51, v235
	v_cvt_pk_bf16_f32 v48, v48, v49
	v_cvt_pk_bf16_f32 v49, v50, v51
	global_store_dwordx2 v[140:141], v[48:49], off
	s_waitcnt vmcnt(31)
	v_add_f32_e32 v40, v40, v236
	v_add_f32_e32 v41, v41, v237
	v_add_f32_e32 v42, v42, v238
	v_add_f32_e32 v43, v43, v239
	v_cvt_pk_bf16_f32 v40, v40, v41
	v_cvt_pk_bf16_f32 v41, v42, v43
	global_store_dwordx2 v[140:141], v[40:41], off offset:32
	s_waitcnt vmcnt(31)
	v_add_f32_e32 v36, v36, v240
	v_add_f32_e32 v37, v37, v241
	v_add_f32_e32 v38, v38, v242
	v_add_f32_e32 v39, v39, v243
	v_cvt_pk_bf16_f32 v36, v36, v37
	v_cvt_pk_bf16_f32 v37, v38, v39
	global_store_dwordx2 v[140:141], v[36:37], off offset:256
	s_waitcnt vmcnt(31)
	v_add_f32_e32 v28, v28, v244
	v_add_f32_e32 v29, v29, v245
	v_add_f32_e32 v30, v30, v246
	v_add_f32_e32 v31, v31, v247
	v_cvt_pk_bf16_f32 v28, v28, v29
	v_cvt_pk_bf16_f32 v29, v30, v31
	global_store_dwordx2 v[140:141], v[28:29], off offset:288
	v_lshl_add_u64 v[140:141], v[140:141], 0, s[98:99]
	s_waitcnt vmcnt(23)
	v_add_f32_e32 v32, v32, v124
	v_add_f32_e32 v33, v33, v125
	v_add_f32_e32 v34, v34, v126
	v_add_f32_e32 v35, v35, v127
	v_cvt_pk_bf16_f32 v32, v32, v33
	v_cvt_pk_bf16_f32 v33, v34, v35
	global_store_dwordx2 v[140:141], v[32:33], off
	s_waitcnt vmcnt(23)
	v_add_f32_e32 v24, v24, v120
	v_add_f32_e32 v25, v25, v121
	v_add_f32_e32 v26, v26, v122
	v_add_f32_e32 v27, v27, v123
	v_cvt_pk_bf16_f32 v24, v24, v25
	v_cvt_pk_bf16_f32 v25, v26, v27
	global_store_dwordx2 v[140:141], v[24:25], off offset:32
	s_waitcnt vmcnt(23)
	v_add_f32_e32 v20, v20, v116
	v_add_f32_e32 v21, v21, v117
	v_add_f32_e32 v22, v22, v118
	v_add_f32_e32 v23, v23, v119
	v_cvt_pk_bf16_f32 v20, v20, v21
	v_cvt_pk_bf16_f32 v21, v22, v23
	global_store_dwordx2 v[140:141], v[20:21], off offset:256
	s_waitcnt vmcnt(23)
	v_add_f32_e32 v12, v12, v108
	v_add_f32_e32 v13, v13, v109
	v_add_f32_e32 v14, v14, v110
	v_add_f32_e32 v15, v15, v111
	v_cvt_pk_bf16_f32 v12, v12, v13
	v_cvt_pk_bf16_f32 v13, v14, v15
	global_store_dwordx2 v[140:141], v[12:13], off offset:288
	v_lshl_add_u64 v[140:141], v[140:141], 0, s[98:99]
	s_waitcnt vmcnt(23)
	v_add_f32_e32 v16, v16, v112
	v_add_f32_e32 v17, v17, v113
	v_add_f32_e32 v18, v18, v114
	v_add_f32_e32 v19, v19, v115
	v_cvt_pk_bf16_f32 v16, v16, v17
	v_cvt_pk_bf16_f32 v17, v18, v19
	global_store_dwordx2 v[140:141], v[16:17], off
	s_waitcnt vmcnt(23)
	v_add_f32_e32 v8, v8, v104
	v_add_f32_e32 v9, v9, v105
	v_add_f32_e32 v10, v10, v106
	v_add_f32_e32 v11, v11, v107
	v_cvt_pk_bf16_f32 v8, v8, v9
	v_cvt_pk_bf16_f32 v9, v10, v11
	global_store_dwordx2 v[140:141], v[8:9], off offset:32
	s_waitcnt vmcnt(23)
	v_add_f32_e32 v4, v4, v100
	v_add_f32_e32 v5, v5, v101
	v_add_f32_e32 v6, v6, v102
	v_add_f32_e32 v7, v7, v103
	v_cvt_pk_bf16_f32 v4, v4, v5
	v_cvt_pk_bf16_f32 v5, v6, v7
	global_store_dwordx2 v[140:141], v[4:5], off offset:256
	s_waitcnt vmcnt(23)
	v_add_f32_e32 v0, v0, v92
	v_add_f32_e32 v1, v1, v93
	v_add_f32_e32 v2, v2, v94
	v_add_f32_e32 v3, v3, v95
	v_cvt_pk_bf16_f32 v0, v0, v1
	v_cvt_pk_bf16_f32 v1, v2, v3
	global_store_dwordx2 v[140:141], v[0:1], off offset:288
	s_andn2_b64 vcc, exec, s[38:39]
	s_mov_b64 s[16:17], -1
	s_cbranch_vccnz .LBB0_949
	s_andn2_b64 vcc, exec, s[24:25]
	s_cbranch_vccnz .LBB0_948
	s_barrier
	s_branch .LBB0_948

	.amdhsa_kernel _Z8fwd_mega4Args
		.amdhsa_group_segment_fixed_size 0
		.amdhsa_private_segment_fixed_size 0
		.amdhsa_kernarg_size 392
		.amdhsa_user_sgpr_count 2
		.amdhsa_user_sgpr_dispatch_ptr 0
		.amdhsa_user_sgpr_queue_ptr 0
		.amdhsa_user_sgpr_kernarg_segment_ptr 1
		.amdhsa_user_sgpr_dispatch_id 0
		.amdhsa_user_sgpr_kernarg_preload_length 0
		.amdhsa_user_sgpr_kernarg_preload_offset 0
		.amdhsa_user_sgpr_private_segment_size 0
		.amdhsa_uses_dynamic_stack 0
		.amdhsa_enable_private_segment 0
		.amdhsa_system_sgpr_workgroup_id_x 1
		.amdhsa_system_sgpr_workgroup_id_y 0
		.amdhsa_system_sgpr_workgroup_id_z 0
		.amdhsa_system_sgpr_workgroup_info 0
		.amdhsa_system_vgpr_workitem_id 0
		.amdhsa_next_free_vgpr 256
		.amdhsa_next_free_sgpr 102
		.amdhsa_accum_offset 256
		.amdhsa_reserve_vcc 1
		.amdhsa_float_round_mode_32 0
		.amdhsa_float_round_mode_16_64 0
		.amdhsa_float_denorm_mode_32 3
		.amdhsa_float_denorm_mode_16_64 3
		.amdhsa_dx10_clamp 1
		.amdhsa_ieee_mode 1
		.amdhsa_fp16_overflow 0
		.amdhsa_tg_split 0
		.amdhsa_exception_fp_ieee_invalid_op 0
		.amdhsa_exception_fp_denorm_src 0
		.amdhsa_exception_fp_ieee_div_zero 0
		.amdhsa_exception_fp_ieee_overflow 0
		.amdhsa_exception_fp_ieee_underflow 0
		.amdhsa_exception_fp_ieee_inexact 0
		.amdhsa_exception_int_div_zero 0
	.end_amdhsa_kernel

amdhsa.kernels:
  - .agpr_count:     0
    .args:
      - .offset:         0
        .size:           136
        .value_kind:     by_value
      - .offset:         136
        .size:           4
        .value_kind:     hidden_block_count_x
      - .offset:         140
        .size:           4
        .value_kind:     hidden_block_count_y
      - .offset:         144
        .size:           4
        .value_kind:     hidden_block_count_z
      - .offset:         148
        .size:           2
        .value_kind:     hidden_group_size_x
      - .offset:         150
        .size:           2
        .value_kind:     hidden_group_size_y
      - .offset:         152
        .size:           2
        .value_kind:     hidden_group_size_z
      - .offset:         154
        .size:           2
        .value_kind:     hidden_remainder_x
      - .offset:         156
        .size:           2
        .value_kind:     hidden_remainder_y
      - .offset:         158
        .size:           2
        .value_kind:     hidden_remainder_z
      - .offset:         176
        .size:           8
        .value_kind:     hidden_global_offset_x
      - .offset:         184
        .size:           8
        .value_kind:     hidden_global_offset_y
      - .offset:         192
        .size:           8
        .value_kind:     hidden_global_offset_z
      - .offset:         200
        .size:           2
        .value_kind:     hidden_grid_dims
      - .offset:         256
        .size:           4
        .value_kind:     hidden_dynamic_lds_size
    .group_segment_fixed_size: 0
    .kernarg_segment_align: 8
    .kernarg_segment_size: 392
    .language:       OpenCL C
    .language_version:
      - 2
      - 0
    .max_flat_workgroup_size: 512
    .name:           _Z8fwd_mega4Args
    .private_segment_fixed_size: 0
    .sgpr_count:     108
    .sgpr_spill_count: 0
    .symbol:         _Z8fwd_mega4Args.kd
    .uniform_work_group_size: 1
    .uses_dynamic_stack: false
    .vgpr_count:     256
    .vgpr_spill_count: 0
    .wavefront_size: 64
